# GEMM unit top: counted vmcnt(4) instead of full drain of the previous unit's epilogue stores (staged K-tiles are older in issue order)
# baseline (speedup 1.0000x reference)
; DEV void phase_gemm(const Params& p, int l, int mode) {
;     ...
;   const int wid = tid >> 6, lane = tid & 63, wr = wid >> 2, wc = wid & 3, fr = lane & 15, fq = lane >> 4;
;   const bool last = (l == DEPTH - 1);
;   unsigned voff0, voff1;
;   { int r_, c_; stage_rc(tid * 16, r_, c_); voff0 = (unsigned)(r_ * G_K + c_) * 2u; stage_rc(tid * 16 + 8192, r_, c_); voff1 = (unsigned)(r_ * G_K + c_) * 2u; }
;     ...
;   have = advance(cur);
;   if (have) { G_STAGE7(cur); }
.LBB0_206:
	s_andn2_b64 vcc, exec, s[12:13]
	v_readlane_b32 s80, v255, 38
	s_cbranch_vccnz .LBB0_905
	v_bfe_i32 v3, v0, 27, 1
	v_lshlrev_b32_e32 v1, 4, v0
	v_lshrrev_b32_e32 v3, 22, v3
	v_add_u32_e32 v3, v1, v3
	v_and_b32_e32 v3, 0xfffffc00, v3
	v_sub_u32_e32 v3, v1, v3
	v_lshrrev_b32_e32 v4, 4, v3
	v_bitop3_b32 v4, v4, v3, 32 bitop3:0x6c
	v_ashrrev_i32_e32 v3, 31, v3
	v_ashrrev_i32_e32 v2, 31, v0
	v_lshrrev_b32_e32 v3, 26, v3
	v_lshrrev_b32_e32 v2, 26, v2
	v_add_u32_e32 v3, v4, v3
	v_add_u32_e32 v2, v0, v2
	v_ashrrev_i32_e32 v3, 6, v3
	v_ashrrev_i32_e32 v2, 6, v2
	v_mul_i32_i24_e32 v6, 64, v3
	v_lshlrev_b32_e32 v5, 3, v2
	v_lshlrev_b32_e32 v2, 5, v2
	v_sub_u32_e32 v4, v4, v6
	v_mov_b32_e32 v7, 1
	v_and_b32_e32 v5, 0x1ffff0, v5
	v_and_b32_e32 v2, 32, v2
	v_ashrrev_i16_sdwa v4, v7, sext(v4) dst_sel:DWORD dst_unused:UNUSED_PAD src0_sel:DWORD src1_sel:BYTE_0
	v_add_u32_sdwa v2, v2, sext(v4) dst_sel:DWORD dst_unused:UNUSED_PAD src0_sel:DWORD src1_sel:WORD_0
	v_add_lshl_u32 v3, v3, v5, 11
	v_lshl_add_u32 v198, v2, 1, v3
	v_add_u32_e32 v2, 0x2000, v1
	v_ashrrev_i32_e32 v3, 31, v2
	v_lshrrev_b32_e32 v3, 22, v3
	v_add_u32_e32 v3, v2, v3
	v_ashrrev_i32_e32 v3, 10, v3
	v_mul_i32_i24_e32 v4, 0x400, v3
	v_sub_u32_e32 v2, v2, v4
	v_lshrrev_b32_e32 v4, 4, v2
	v_bitop3_b32 v2, v4, v2, 32 bitop3:0x6c
	v_ashrrev_i32_e32 v5, 31, v2
	v_lshrrev_b32_e32 v5, 26, v5
	v_add_u32_e32 v5, v2, v5
	v_lshrrev_b32_e32 v6, 6, v5
	v_and_b32_e32 v5, 0xc0, v5
	s_add_i32 s2, 0, 0x10000
	v_lshlrev_b32_e32 v4, 3, v3
	v_lshlrev_b32_e32 v3, 5, v3
	v_sub_u32_e32 v2, v2, v5
	v_add_u32_e32 v200, s2, v1
	v_and_b32_e32 v4, 0x1ffff0, v4
	v_and_b32_e32 v3, 32, v3
	v_ashrrev_i16_sdwa v2, v7, sext(v2) dst_sel:DWORD dst_unused:UNUSED_PAD src0_sel:DWORD src1_sel:BYTE_0
	v_readfirstlane_b32 s3, v200
	v_add_u32_e32 v201, 0x2000, v200
	v_add_u32_sdwa v2, v3, sext(v2) dst_sel:DWORD dst_unused:UNUSED_PAD src0_sel:DWORD src1_sel:WORD_0
	v_add_lshl_u32 v3, v6, v4, 11
	s_and_b32 s9, s73, 0xffff
	s_mov_b32 s8, s72
	s_mov_b32 s10, s70
	s_mov_b32 s11, s71
	s_lshl_b32 s1, s95, 11
	s_mov_b32 m0, s3
	v_readfirstlane_b32 s3, v201
	v_add_u32_e32 v202, 0, v1
	v_lshl_add_u32 v199, v2, 1, v3
	buffer_load_dwordx4 v198, s[8:11], s1 offen lds
	s_mov_b32 m0, s3
	v_readfirstlane_b32 s4, v202
	v_add_u32_e32 v203, 0x2000, v202
	v_readlane_b32 s16, v254, 13
	s_and_b32 s13, s69, 0xffff
	s_mov_b32 s12, s68
	s_mov_b32 s14, s70
	s_mov_b32 s15, s71
	buffer_load_dwordx4 v199, s[8:11], s1 offen lds
	s_lshl_b32 s3, s67, 11
	s_mov_b32 m0, s4
	v_readfirstlane_b32 s4, v203
	v_add_u32_e32 v204, s16, v1
	buffer_load_dwordx4 v198, s[12:15], s3 offen lds
	s_mov_b32 m0, s4
	v_readfirstlane_b32 s5, v204
	v_add_u32_e32 v205, 0x2000, v204
	buffer_load_dwordx4 v199, s[12:15], s3 offen lds
	s_add_i32 s4, s1, 0x40000
	s_mov_b32 m0, s5
	v_readfirstlane_b32 s5, v205
	v_add_u32_e32 v206, 0x4000, v202
	buffer_load_dwordx4 v198, s[8:11], s4 offen lds
	s_mov_b32 m0, s5
	v_readfirstlane_b32 s5, v206
	v_add_u32_e32 v207, 0x6000, v202
	v_readlane_b32 s17, v254, 14
	buffer_load_dwordx4 v199, s[8:11], s4 offen lds
	s_add_i32 s4, s3, 0x40000
	s_mov_b32 m0, s5
	v_readfirstlane_b32 s5, v207
	v_add_u32_e32 v208, s17, v1
	buffer_load_dwordx4 v198, s[12:15], s4 offen lds
	s_mov_b32 m0, s5
	v_readfirstlane_b32 s5, v208
	v_add_u32_e32 v209, 0x2000, v208
	buffer_load_dwordx4 v199, s[12:15], s4 offen lds
	s_or_b32 s4, s1, 0x80
	s_mov_b32 m0, s5
	v_readfirstlane_b32 s5, v209
	buffer_load_dwordx4 v198, s[8:11], s4 offen lds
	s_mov_b32 m0, s5
	v_add_u32_e32 v210, 0x8000, v202
	buffer_load_dwordx4 v199, s[8:11], s4 offen lds
	v_readfirstlane_b32 s4, v210
	v_add_u32_e32 v211, 0xa000, v202
	s_bitset1_b32 s3, 7
	s_mov_b32 m0, s4
	v_readfirstlane_b32 s4, v211
	buffer_load_dwordx4 v198, s[12:15], s3 offen lds
	s_mov_b32 m0, s4
	v_readlane_b32 s4, v254, 15
	buffer_load_dwordx4 v199, s[12:15], s3 offen lds
	s_add_i32 s1, s1, 0x40080
	v_add_u32_e32 v212, s4, v1
	v_add_u32_e32 v213, 0x2000, v212
	v_readfirstlane_b32 s3, v212
	s_mov_b32 m0, s3
	v_readfirstlane_b32 s3, v213
	buffer_load_dwordx4 v198, s[8:11], s1 offen lds
	s_mov_b32 m0, s3
	v_ashrrev_i32_e32 v1, 8, v0
	buffer_load_dwordx4 v199, s[8:11], s1 offen lds
	s_mul_i32 s1, s76, 5
	v_and_b32_e32 v2, 15, v0
	v_lshlrev_b32_e32 v4, 2, v0
	v_writelane_b32 v255, s1, 39
	v_and_b32_e32 v3, 48, v0
	v_cmp_eq_u32_e64 s[8:9], 1, v1
	v_lshlrev_b32_e32 v2, 6, v2
	v_and_b32_e32 v4, 32, v4
	v_writelane_b32 v255, s8, 33
	v_bitop3_b32 v2, v2, v4, v3 bitop3:0x36
	s_movk_i32 s1, 0x100
	v_writelane_b32 v255, s9, 34
	v_add_u32_e32 v5, s2, v2
	v_cmp_gt_u32_e64 s[2:3], s1, v0
	v_lshlrev_b32_e32 v0, 6, v0
	s_movk_i32 s1, 0x3c0
	v_writelane_b32 v255, s2, 27
	v_and_b32_e32 v9, 0x3000, v0
	v_lshlrev_b32_e32 v1, 13, v1
	v_writelane_b32 v255, s3, 28
	v_and_or_b32 v0, v0, s1, v3
	v_readlane_b32 s80, v255, 38
	v_writelane_b32 v255, s29, 40
	v_writelane_b32 v255, s46, 41
	v_add_u32_e32 v6, s16, v2
	v_add_u32_e32 v7, s17, v2
	v_add_u32_e32 v8, s4, v2
	v_add_u32_e32 v2, 0, v2
	v_xad_u32 v0, v0, v4, 0
	v_or_b32_e32 v3, 0x800, v1
	v_or_b32_e32 v4, 0x1000, v1
	v_or_b32_e32 v10, 0x1800, v1
	v_writelane_b32 v255, s48, 35
	v_add_u32_e32 v214, 0xc000, v202
	v_add_u32_e32 v215, 0xe000, v202
	v_add_u32_e32 v216, v5, v9
	v_add_u32_e32 v217, v2, v1
	v_add_u32_e32 v218, v0, v3
	v_add_u32_e32 v219, v0, v4
	v_add_u32_e32 v220, v0, v10
	v_add_u32_e32 v221, v6, v9
	v_add_u32_e32 v222, v7, v9
	v_add_u32_e32 v223, v8, v9
	v_writelane_b32 v255, s49, 36
	s_waitcnt vmcnt(0)

; #define WAIT_V(n) asm volatile("s_waitcnt vmcnt(" #n ")" ::: "memory")
; #define G_BAR __builtin_amdgcn_s_barrier()
; DEV void phase_gemm(const Params& p, int l, int mode) {
;     ...
;     f32x4 acc[2][2][4][2] = {};
;     bf16x8 At[4][2], B0[2][2], B1[2][2];
;     constexpr int nt = G_K / G_BK;
;     if (wr == 1) G_BAR;
;     WAIT_V(0); G_BAR;
;     G_BAR;
.LBB0_210:
	s_or_b64 exec, exec, s[8:9]
	s_waitcnt vmcnt(4)
	v_mov_b32_e32 v0, 0
	s_and_b32 s69, s69, 0xffff
	s_and_b32 s73, s73, 0xffff
	s_lshl_b32 s8, s67, 11
	s_lshl_b32 s9, s95, 11
	s_mov_b32 s10, -2
	s_mov_b32 s11, 0
	v_mov_b32_e32 v1, v0
	v_mov_b32_e32 v2, v0
	v_mov_b32_e32 v3, v0
	v_mov_b32_e32 v4, v0
	v_mov_b32_e32 v5, v0
	v_mov_b32_e32 v6, v0
	v_mov_b32_e32 v7, v0
	v_mov_b32_e32 v8, v0
	v_mov_b32_e32 v9, v0
	v_mov_b32_e32 v10, v0
	v_mov_b32_e32 v11, v0
	v_mov_b32_e32 v12, v0
	v_mov_b32_e32 v13, v0
	v_mov_b32_e32 v14, v0
	v_mov_b32_e32 v15, v0
	v_mov_b32_e32 v16, v0
	v_mov_b32_e32 v17, v0
	v_mov_b32_e32 v18, v0
	v_mov_b32_e32 v19, v0
	v_mov_b32_e32 v20, v0
	v_mov_b32_e32 v21, v0
	v_mov_b32_e32 v22, v0
	v_mov_b32_e32 v23, v0
	v_mov_b32_e32 v24, v0
	v_mov_b32_e32 v25, v0
	v_mov_b32_e32 v26, v0
	v_mov_b32_e32 v27, v0
	v_mov_b32_e32 v28, v0
	v_mov_b32_e32 v29, v0
	v_mov_b32_e32 v30, v0
	v_mov_b32_e32 v31, v0
	v_mov_b32_e32 v32, v0
	v_mov_b32_e32 v33, v0
	v_mov_b32_e32 v34, v0
	v_mov_b32_e32 v35, v0
	v_mov_b32_e32 v36, v0
	v_mov_b32_e32 v37, v0
	v_mov_b32_e32 v38, v0
	v_mov_b32_e32 v39, v0
	v_mov_b32_e32 v40, v0
	v_mov_b32_e32 v41, v0
	v_mov_b32_e32 v42, v0
	v_mov_b32_e32 v43, v0
	v_mov_b32_e32 v44, v0
	v_mov_b32_e32 v45, v0
	v_mov_b32_e32 v46, v0
	v_mov_b32_e32 v47, v0
	v_mov_b32_e32 v48, v0
	v_mov_b32_e32 v49, v0
	v_mov_b32_e32 v50, v0
	v_mov_b32_e32 v51, v0
	v_mov_b32_e32 v52, v0
	v_mov_b32_e32 v53, v0
	v_mov_b32_e32 v54, v0
	v_mov_b32_e32 v55, v0
	v_mov_b32_e32 v56, v0
	v_mov_b32_e32 v57, v0
	v_mov_b32_e32 v58, v0
	v_mov_b32_e32 v59, v0
	v_mov_b32_e32 v60, v0
	v_mov_b32_e32 v61, v0
	v_mov_b32_e32 v62, v0
	v_mov_b32_e32 v63, v0
	v_mov_b32_e32 v64, v0
	v_mov_b32_e32 v65, v0
	v_mov_b32_e32 v66, v0
	v_mov_b32_e32 v67, v0
	v_mov_b32_e32 v68, v0
	v_mov_b32_e32 v69, v0
	v_mov_b32_e32 v70, v0
	v_mov_b32_e32 v71, v0
	v_mov_b32_e32 v72, v0
	v_mov_b32_e32 v73, v0
	v_mov_b32_e32 v74, v0
	v_mov_b32_e32 v75, v0
	v_mov_b32_e32 v76, v0
	v_mov_b32_e32 v77, v0
	v_mov_b32_e32 v78, v0
	v_mov_b32_e32 v79, v0
	v_mov_b32_e32 v80, v0
	v_mov_b32_e32 v81, v0
	v_mov_b32_e32 v82, v0
	v_mov_b32_e32 v83, v0
	v_mov_b32_e32 v84, v0
	v_mov_b32_e32 v85, v0
	v_mov_b32_e32 v86, v0
	v_mov_b32_e32 v87, v0
	v_mov_b32_e32 v88, v0
	v_mov_b32_e32 v89, v0
	v_mov_b32_e32 v90, v0
	v_mov_b32_e32 v91, v0
	v_mov_b32_e32 v92, v0
	v_mov_b32_e32 v93, v0
	v_mov_b32_e32 v94, v0
	v_mov_b32_e32 v95, v0
	v_mov_b32_e32 v96, v0
	v_mov_b32_e32 v97, v0
	v_mov_b32_e32 v98, v0
	v_mov_b32_e32 v99, v0
	v_mov_b32_e32 v100, v0
	v_mov_b32_e32 v101, v0
	v_mov_b32_e32 v102, v0
	v_mov_b32_e32 v103, v0
	v_mov_b32_e32 v104, v0
	v_mov_b32_e32 v105, v0
	v_mov_b32_e32 v106, v0
	v_mov_b32_e32 v107, v0
	v_mov_b32_e32 v108, v0
	v_mov_b32_e32 v109, v0
	v_mov_b32_e32 v110, v0
	v_mov_b32_e32 v111, v0
	v_mov_b32_e32 v112, v0
	v_mov_b32_e32 v113, v0
	v_mov_b32_e32 v114, v0
	v_mov_b32_e32 v115, v0
	v_mov_b32_e32 v116, v0
	v_mov_b32_e32 v117, v0
	v_mov_b32_e32 v118, v0
	v_mov_b32_e32 v119, v0
	v_mov_b32_e32 v120, v0
	v_mov_b32_e32 v121, v0
	v_mov_b32_e32 v122, v0
	v_mov_b32_e32 v123, v0
	v_mov_b32_e32 v124, v0
	v_mov_b32_e32 v125, v0
	v_mov_b32_e32 v126, v0
	v_mov_b32_e32 v127, v0
	s_barrier
	s_barrier
